# cand2 shifted by 2 s_nop at entry (code placement check)
# baseline (speedup 1.0000x reference)
; #define LAS __attribute__((address_space(3)))
; __global__ void __launch_bounds__(NWAVES * 64, 2) skel_fwd(Args args) {
;     ...
;     F.lds = (LAS unsigned char*)lds;
;     F.MISC = (volatile LAS unsigned*)(F.lds + MISC_OFF);
;     F.tid = threadIdx.x; F.lane = F.tid & 63; F.wave = __builtin_amdgcn_readfirstlane(F.tid >> 6);
;     F.G = gridDim.x; { const int bx = blockIdx.x; F.vcu = (F.G % 8 == 0) ? (bx % 8) * (F.G / 8) + bx / 8 : bx; }
_Z8skel_fwd4Args:
	s_nop 0
	s_nop 0
	s_load_dword s76, s[0:1], 0x98
	s_mov_b32 s73, s2
	s_add_u32 s2, s0, 0x98
	s_addc_u32 s3, s1, 0
	s_mov_b32 s78, s73
	v_writelane_b32 v243, s2, 0
	s_nop 1
	v_writelane_b32 v243, s3, 1
	s_waitcnt lgkmcnt(0)
	s_and_b32 s2, s76, 7
	s_cmp_lg_u32 s2, 0
	s_cbranch_scc1 .LBB0_2
	s_ashr_i32 s3, s73, 31
	s_lshr_b32 s3, s3, 29
	s_add_i32 s3, s73, s3
	s_and_b32 s4, s3, -8
	s_ashr_i32 s2, s76, 3
	s_sub_i32 s4, s73, s4
	s_mul_i32 s2, s2, s4
	s_ashr_i32 s3, s3, 3
	s_add_i32 s78, s2, s3
